# FFN-up meta-row tail unit: 8 row-statistic loads hoisted to unit start (fresh registers), removing two more serialized round trips; on v36
# baseline (speedup 1.0000x reference)
.LBB0_954:
	s_and_b32 s17, s3, 0xffffff00
	s_and_b32 s16, s1, 0x60
	v_or_b32_e32 v2, s17, v1
	v_or_b32_e32 v2, s16, v2
	v_ashrrev_i32_e32 v3, 31, v2
	v_lshlrev_b64 v[2:3], 11, v[2:3]
	v_lshl_add_u64 v[86:87], v[36:37], 0, v[2:3]
	global_load_dwordx4 v[18:21], v[34:35], off
	global_load_dwordx4 v[2:5], v[86:87], off
	v_add_co_u32_e32 v90, vcc, 0x40000, v86
	s_ashr_i32 s17, s0, 2
	s_nop 0
	v_addc_co_u32_e32 v91, vcc, 0, v87, vcc
	global_load_dwordx4 v[22:25], v[90:91], off
	global_load_dwordx4 v[46:49], v[34:35], off offset:32
	global_load_dwordx4 v[50:53], v[86:87], off offset:32
	global_load_dwordx4 v[54:57], v[90:91], off offset:32
	global_load_dwordx4 v[58:61], v[34:35], off offset:64
	global_load_dwordx4 v[62:65], v[86:87], off offset:64
	global_load_dwordx4 v[66:69], v[90:91], off offset:64
	global_load_dwordx4 v[70:73], v[34:35], off offset:96
	global_load_dwordx4 v[74:77], v[86:87], off offset:96
	global_load_dwordx4 v[78:81], v[90:91], off offset:96
	s_lshl_b32 s18, s17, 8
	s_or_b32 s18, s18, s16
	s_lshl_b32 s17, s17, 7
	s_or_b32 s16, s17, s16
	s_addk_i32 s1, 0x2000
	s_addk_i32 s3, 0x4000
	s_waitcnt vmcnt(0) lgkmcnt(0)
	v_mfma_f32_32x32x16_bf16 v[2:17], v[18:21], v[2:5], 0
	v_mfma_f32_32x32x16_bf16 v[18:33], v[18:21], v[22:25], 0
	v_mfma_f32_32x32x16_bf16 v[2:17], v[46:49], v[50:53], v[2:17]
	v_mfma_f32_32x32x16_bf16 v[18:33], v[46:49], v[54:57], v[18:33]
	v_mfma_f32_32x32x16_bf16 v[2:17], v[58:61], v[62:65], v[2:17]
	v_mfma_f32_32x32x16_bf16 v[18:33], v[58:61], v[66:69], v[18:33]
	v_mfma_f32_32x32x16_bf16 v[2:17], v[70:73], v[74:77], v[2:17]
	v_mfma_f32_32x32x16_bf16 v[18:33], v[70:73], v[78:81], v[18:33]
	global_load_dwordx4 v[46:49], v[34:35], off offset:128
	global_load_dwordx4 v[50:53], v[86:87], off offset:128
	global_load_dwordx4 v[54:57], v[90:91], off offset:128
	global_load_dwordx4 v[58:61], v[34:35], off offset:160
	global_load_dwordx4 v[62:65], v[86:87], off offset:160
	global_load_dwordx4 v[66:69], v[90:91], off offset:160
	global_load_dwordx4 v[70:73], v[34:35], off offset:192
	global_load_dwordx4 v[74:77], v[86:87], off offset:192
	global_load_dwordx4 v[78:81], v[90:91], off offset:192
	global_load_dwordx4 v[82:85], v[34:35], off offset:224
	s_nop 0
	global_load_dwordx4 v[86:89], v[86:87], off offset:224
	s_nop 0
	global_load_dwordx4 v[90:93], v[90:91], off offset:224
	s_waitcnt vmcnt(0) lgkmcnt(0)
	v_mfma_f32_32x32x16_bf16 v[2:17], v[46:49], v[50:53], v[2:17]
	v_mfma_f32_32x32x16_bf16 v[18:33], v[46:49], v[54:57], v[18:33]
	v_or_b32_e32 v46, s18, v43
	v_ashrrev_i32_e32 v47, 31, v46
	v_lshlrev_b64 v[94:95], 3, v[46:47]
	v_lshl_add_u64 v[96:97], s[10:11], 0, v[94:95]
	v_lshl_add_u64 v[94:95], s[12:13], 0, v[94:95]
	global_load_dwordx4 v[98:101], v[96:97], off
	global_load_dwordx4 v[102:105], v[94:95], off
	global_load_dwordx4 v[106:109], v[96:97], off offset:1024
	global_load_dwordx4 v[110:113], v[94:95], off offset:1024
	global_load_dwordx4 v[114:117], v[38:39], off
	global_load_dwordx4 v[118:121], v[38:39], off offset:16
	global_load_dwordx4 v[122:125], v[38:39], off offset:32
	global_load_dwordx4 v[126:129], v[38:39], off offset:48
	global_load_dwordx4 v[130:133], v[38:39], off offset:64
	global_load_dwordx4 v[134:137], v[38:39], off offset:80
	global_load_dwordx4 v[138:141], v[38:39], off offset:96
	global_load_dwordx4 v[142:145], v[38:39], off offset:112
	v_mfma_f32_32x32x16_bf16 v[2:17], v[58:61], v[62:65], v[2:17]
	v_mfma_f32_32x32x16_bf16 v[18:33], v[58:61], v[66:69], v[18:33]
	v_mfma_f32_32x32x16_bf16 v[2:17], v[70:73], v[74:77], v[2:17]
	v_mfma_f32_32x32x16_bf16 v[18:33], v[70:73], v[78:81], v[18:33]
	v_mfma_f32_32x32x16_bf16 v[2:17], v[82:85], v[86:89], v[2:17]
	v_mfma_f32_32x32x16_bf16 v[18:33], v[82:85], v[90:93], v[18:33]
	s_nop 11
	ds_write2_b32 v42, v2, v18 offset1:32
	ds_write2_b32 v42, v3, v19 offset0:64 offset1:96
	ds_write2_b32 v42, v4, v20 offset0:128 offset1:160
	ds_write2_b32 v42, v5, v21 offset0:192 offset1:224
	v_add_u32_e32 v2, 0x800, v42
	ds_write2_b32 v2, v6, v22 offset1:32
	ds_write2_b32 v2, v7, v23 offset0:64 offset1:96
	ds_write2_b32 v2, v8, v24 offset0:128 offset1:160
	ds_write2_b32 v2, v9, v25 offset0:192 offset1:224
	v_add_u32_e32 v2, 0x1000, v42
	ds_write2_b32 v2, v10, v26 offset1:32
	ds_write2_b32 v2, v11, v27 offset0:64 offset1:96
	ds_write2_b32 v2, v12, v28 offset0:128 offset1:160
	ds_write2_b32 v2, v13, v29 offset0:192 offset1:224
	v_add_u32_e32 v2, 0x1800, v42
	ds_write2_b32 v2, v14, v30 offset1:32
	ds_write2_b32 v2, v15, v31 offset0:64 offset1:96
	ds_write2_b32 v2, v16, v32 offset0:128 offset1:160
	ds_write2_b32 v2, v17, v33 offset0:192 offset1:224
	s_waitcnt lgkmcnt(0)
	s_barrier
	ds_read2_b64 v[2:5], v44 offset1:16
	s_waitcnt lgkmcnt(0)
	v_pk_add_f32 v[32:33], v[4:5], 0 op_sel_hi:[1,0]
	v_add_u32_e32 v4, 0x2000, v44
	ds_read2_b64 v[12:15], v4 offset1:16
	s_waitcnt vmcnt(0)
	v_mov_b64_e32 v[4:5], v[114:115]
	v_mov_b64_e32 v[6:7], v[116:117]
	v_mov_b64_e32 v[8:9], v[118:119]
	v_mov_b64_e32 v[10:11], v[120:121]
	v_mov_b64_e32 v[16:17], v[122:123]
	v_mov_b64_e32 v[18:19], v[124:125]
	v_mov_b64_e32 v[20:21], v[126:127]
	v_mov_b64_e32 v[22:23], v[128:129]
	v_mov_b64_e32 v[24:25], v[130:131]
	v_mov_b64_e32 v[26:27], v[132:133]
	v_mov_b64_e32 v[28:29], v[134:135]
	v_mov_b64_e32 v[30:31], v[136:137]
	v_pk_add_f32 v[2:3], v[2:3], 0 op_sel_hi:[1,0]
	s_waitcnt vmcnt(0) lgkmcnt(0)
	v_pk_add_f32 v[4:5], v[4:5], v[6:7]
	s_nop 0
	v_pk_add_f32 v[4:5], v[4:5], 0 op_sel_hi:[1,0]
	v_pk_add_f32 v[6:7], v[8:9], v[10:11]
	v_pk_add_f32 v[12:13], v[2:3], v[12:13]
	v_add_f32_e32 v49, v25, v27
	v_mov_b32_e32 v25, v28
	v_mov_b32_e32 v27, v30
	v_pk_add_f32 v[50:51], v[24:25], v[26:27]
	v_add_f32_e32 v53, v29, v31
	v_mov_b64_e32 v[24:25], v[138:139]
	v_mov_b64_e32 v[26:27], v[140:141]
	v_mov_b64_e32 v[28:29], v[142:143]
	v_mov_b64_e32 v[30:31], v[144:145]
	v_pk_add_f32 v[4:5], v[4:5], v[6:7]
	v_pk_add_f32 v[6:7], v[16:17], v[18:19]
	v_mov_b32_e32 v48, v50
	v_pk_add_f32 v[4:5], v[4:5], v[6:7]
	v_pk_add_f32 v[6:7], v[20:21], v[22:23]
	v_mov_b32_e32 v52, v51
	v_pk_add_f32 v[4:5], v[4:5], v[6:7]
	v_pk_add_f32 v[18:19], v[32:33], v[14:15]
	v_pk_add_f32 v[4:5], v[4:5], v[48:49]
	v_lshlrev_b64 v[8:9], 3, v[46:47]
	v_pk_add_f32 v[4:5], v[4:5], v[52:53]
	v_lshl_add_u64 v[10:11], s[10:11], 0, v[8:9]
	v_lshl_add_u64 v[8:9], s[12:13], 0, v[8:9]
	v_or_b32_e32 v2, s16, v43
	s_add_i32 s16, s0, 0x100
	s_cmpk_lt_i32 s0, 0xff58
	s_mov_b32 s0, s16
	s_waitcnt vmcnt(0) lgkmcnt(0)
	v_add_f32_e32 v55, v25, v27
	v_mov_b32_e32 v25, v28
	v_mov_b32_e32 v27, v30
	v_pk_add_f32 v[24:25], v[24:25], v[26:27]
	v_add_f32_e32 v27, v29, v31
	v_mov_b32_e32 v54, v24
	v_pk_add_f32 v[4:5], v[4:5], v[54:55]
	v_mov_b32_e32 v26, v25
	v_pk_add_f32 v[4:5], v[4:5], v[26:27]
	s_nop 0
	v_pk_mul_f32 v[6:7], v[4:5], s[64:65] op_sel_hi:[1,0]
	s_nop 0
	v_fma_f32 v3, -v6, v6, v7
	v_max_f32_e32 v3, 0, v3
	v_add_f32_e32 v3, 0x3727c5ac, v3
	v_cmp_gt_f32_e32 vcc, s35, v3
	v_mul_f32_e32 v4, 0x4b800000, v3
	s_nop 0
	v_cndmask_b32_e32 v3, v3, v4, vcc
	v_rsq_f32_e32 v3, v3
	s_nop 0
	v_mul_f32_e32 v4, 0x45800000, v3
	v_cndmask_b32_e32 v4, v3, v4, vcc
	v_add_u32_e32 v3, 0x4000, v44
	ds_read2_b64 v[14:17], v3 offset1:16
	v_add_u32_e32 v3, 0x6000, v44
	s_waitcnt lgkmcnt(0)
	v_pk_add_f32 v[20:21], v[12:13], v[14:15]
	ds_read2_b64 v[12:15], v3 offset1:16
	v_pk_add_f32 v[16:17], v[18:19], v[16:17]
	v_add_u32_e32 v3, 0x8000, v44
	s_waitcnt lgkmcnt(0)
	v_pk_add_f32 v[18:19], v[20:21], v[12:13]
	v_pk_add_f32 v[16:17], v[16:17], v[14:15]
	ds_read2_b64 v[12:15], v3 offset1:16
	v_add_u32_e32 v3, 0xa000, v44
	s_waitcnt lgkmcnt(0)
	v_pk_add_f32 v[18:19], v[18:19], v[12:13]
	v_pk_add_f32 v[16:17], v[16:17], v[14:15]
	ds_read2_b64 v[12:15], v3 offset1:16
	v_add_u32_e32 v3, 0xc000, v44
	s_waitcnt lgkmcnt(0)
	v_pk_add_f32 v[18:19], v[18:19], v[12:13]
	v_pk_add_f32 v[16:17], v[16:17], v[14:15]
	ds_read2_b64 v[12:15], v3 offset1:16
	v_add_u32_e32 v3, 0xe000, v44
	s_waitcnt lgkmcnt(0)
	v_pk_add_f32 v[18:19], v[18:19], v[12:13]
	v_pk_add_f32 v[16:17], v[16:17], v[14:15]
	ds_read2_b64 v[12:15], v3 offset1:16
	s_waitcnt lgkmcnt(0)
	v_pk_add_f32 v[18:19], v[18:19], v[12:13]
	v_pk_add_f32 v[16:17], v[16:17], v[14:15]
	v_mov_b64_e32 v[12:13], v[98:99]
	v_mov_b64_e32 v[14:15], v[100:101]
	s_waitcnt vmcnt(0) lgkmcnt(0)
	v_cvt_f64_i32_e32 v[20:21], v15
	v_ldexp_f64 v[20:21], v[20:21], 32
	v_cvt_f64_u32_e32 v[14:15], v14
	v_add_f64 v[14:15], v[20:21], v[14:15]
	v_cvt_f64_i32_e32 v[20:21], v13
	v_ldexp_f64 v[20:21], v[20:21], 32
	v_cvt_f64_u32_e32 v[12:13], v12
	v_add_f64 v[12:13], v[20:21], v[12:13]
	v_ldexp_f64 v[12:13], v[12:13], s2
	v_ldexp_f64 v[14:15], v[14:15], s2
	v_cvt_f32_f64_e32 v15, v[14:15]
	v_cvt_f32_f64_e32 v14, v[12:13]
	v_pk_fma_f32 v[18:19], v[6:7], v[14:15], v[18:19] op_sel_hi:[0,1,1] neg_lo:[1,0,0] neg_hi:[1,0,0]
	v_mov_b64_e32 v[12:13], v[102:103]
	v_mov_b64_e32 v[14:15], v[104:105]
	s_waitcnt vmcnt(0) lgkmcnt(0)
	v_cvt_f64_i32_e32 v[20:21], v15
	v_ldexp_f64 v[20:21], v[20:21], 32
	v_cvt_f64_u32_e32 v[14:15], v14
	v_add_f64 v[14:15], v[20:21], v[14:15]
	v_cvt_f64_i32_e32 v[20:21], v13
	v_ldexp_f64 v[20:21], v[20:21], 32
	v_cvt_f64_u32_e32 v[12:13], v12
	v_add_f64 v[12:13], v[20:21], v[12:13]
	v_ldexp_f64 v[12:13], v[12:13], s2
	v_ldexp_f64 v[14:15], v[14:15], s2
	v_cvt_f32_f64_e32 v15, v[14:15]
	v_cvt_f32_f64_e32 v14, v[12:13]
	v_mov_b64_e32 v[10:11], v[106:107]
	v_mov_b64_e32 v[12:13], v[108:109]
	v_pk_fma_f32 v[14:15], v[18:19], v[4:5], v[14:15] op_sel_hi:[1,0,1]
	s_waitcnt vmcnt(0) lgkmcnt(0)
	v_cvt_f64_i32_e32 v[18:19], v13
	v_ldexp_f64 v[18:19], v[18:19], 32
	v_cvt_f64_u32_e32 v[12:13], v12
	v_add_f64 v[12:13], v[18:19], v[12:13]
	v_cvt_f64_i32_e32 v[18:19], v11
	v_ldexp_f64 v[18:19], v[18:19], 32
	v_cvt_f64_u32_e32 v[10:11], v10
	v_add_f64 v[10:11], v[18:19], v[10:11]
	v_ldexp_f64 v[10:11], v[10:11], s2
	v_ldexp_f64 v[12:13], v[12:13], s2
	v_cvt_f32_f64_e32 v13, v[12:13]
	v_cvt_f32_f64_e32 v12, v[10:11]
	v_pk_fma_f32 v[10:11], v[6:7], v[12:13], v[16:17] op_sel_hi:[0,1,1] neg_lo:[1,0,0] neg_hi:[1,0,0]
	v_mov_b64_e32 v[6:7], v[110:111]
	v_mov_b64_e32 v[8:9], v[112:113]
	v_mul_f32_e32 v3, 0xbfb8aa3b, v14
	v_exp_f32_e32 v3, v3
	s_waitcnt vmcnt(0) lgkmcnt(0)
	v_cvt_f64_i32_e32 v[12:13], v9
	v_ldexp_f64 v[12:13], v[12:13], 32
	v_cvt_f64_u32_e32 v[8:9], v8
	v_add_f64 v[8:9], v[12:13], v[8:9]
	v_cvt_f64_i32_e32 v[12:13], v7
	v_ldexp_f64 v[12:13], v[12:13], 32
	v_cvt_f64_u32_e32 v[6:7], v6
	v_add_f64 v[6:7], v[12:13], v[6:7]
	v_ldexp_f64 v[6:7], v[6:7], s2
	v_ldexp_f64 v[8:9], v[8:9], s2
	v_add_f32_e32 v3, 1.0, v3
	v_cvt_f32_f64_e32 v9, v[8:9]
	v_cvt_f32_f64_e32 v8, v[6:7]
	v_rcp_f32_e32 v6, v3
	v_mul_f32_e32 v3, 0xbfb8aa3b, v15
	v_exp_f32_e32 v3, v3
	v_pk_fma_f32 v[4:5], v[10:11], v[4:5], v[8:9] op_sel_hi:[1,0,1]
	v_add_f32_e32 v3, 1.0, v3
	v_rcp_f32_e32 v7, v3
	v_ashrrev_i32_e32 v3, 31, v2
	v_lshl_add_u64 v[2:3], v[2:3], 1, v[40:41]
	v_pk_mul_f32 v[6:7], v[14:15], v[6:7]
	s_nop 0
	v_pk_mul_f32 v[4:5], v[4:5], v[6:7]
	s_nop 0
	v_cvt_pk_bf16_f32 v4, v4, v5
	global_store_dword v[2:3], v4, off sc1
	s_waitcnt vmcnt(0) lgkmcnt(0)
	s_barrier
	s_cmp_lg_u32 s86, 0
	s_cbranch_scc1 .Ltail_sig_skip
	v_mov_b32_e32 v18, 0x3d00
	s_mov_b64 exec, 1
	global_atomic_add v18, v223, s[90:91]
	s_mov_b64 exec, -1
